# P1 only: prompt FFN1-in on 208 XCD-aligned WGs (7 rounds), 48 WGs copy 22 chunks each
# speedup vs baseline: 1.0145x; 1.0145x over previous
; #define PG8_LAS __attribute__((address_space(3)))
; #define PG8_BAR __builtin_amdgcn_s_barrier()
; template <class Epi, class Sched, bool ALIGN_EPI = false, bool SP2 = false>
; __device__ __forceinline__ void gemm_phase(PG8_LAS unsigned char* lds, const Gemm g, const Sched& S, const Epi& E) {
;     int tid_o = threadIdx.x; asm volatile("" : "+v"(tid_o));
;     const int tid = tid_o, wid = __builtin_amdgcn_readfirstlane(tid >> 6), lane = tid & 63, wr = wid >> 2, wc = wid & 3, fr = lane & 15, fq = lane >> 4;
;     const int K = g.K, nt = K / BK;
;     unsigned voffA[2], voffB[2];
; #pragma unroll
;     for (int i = 0; i < 2; ++i) { int R, C; stage_rc(tid * 16 + i * 8192, R, C); const int Rb = Epi::PERM ? ((R & ~31) + perm32(R & 31)) : R;
;         voffA[i] = (unsigned)(R * K + C) * 2u; voffB[i] = (unsigned)(Rb * K + C) * 2u; }
;     const size_t kstep = (size_t)(BK * 2);
;     const size_t hstep = (size_t)HALF * K * 2;
;     const size_t tstep = 2 * hstep;
;     const unsigned ldsw = (unsigned)wid * 1024u;
;     const int aoff = lds_byte(wr * 64 + fr, fq * 8), boff = lds_byte(wc * 32 + fr, fq * 8);
;     ...
;     Unit cur, nxt; int ui = 0;
;     if (!S.next(0, cur)) return;
;     f32x4 acc[2][2][4][2];
; #pragma unroll
;     for (int a = 0; a < 2; ++a)
; #pragma unroll
;         for (int b = 0; b < 2; ++b)
; #pragma unroll
;             for (int m = 0; m < 4; ++m)
; #pragma unroll
;                 for (int n = 0; n < 2; ++n) acc[a][b][m][n] = (f32x4){0.f, 0.f, 0.f, 0.f};
;     bf16x8 At[4][2], B0[2][2], B1[2][2];
;     const char* cA = (const char*)g.A + (size_t)cur.pm * tstep; const char* cB = (const char*)g.Bt + (size_t)cur.pn * tstep;
;     S.a_ready(cur);
;     if constexpr (SP2) {
;         PG8_STAGE(PG8_SB(0, 0), cB, voffB); PG8_STAGE(PG8_SB(0, 1), cB + hstep, voffB); PG8_STAGE(PG8_SA(0, 0), cA, voffA); PG8_STAGE(PG8_SA(0, 1), cA + hstep, voffA);
;         if (wr == 1) PG8_BAR;
; __global__ void __launch_bounds__(512, 2) mk_fwd(Args args) {
;     ...
;     if (IN(1)) {
;         pg8::EpiSwiGLU E{rss0, ACT};
;         GEMM(pg8::EpiSwiGLU, XB, W1, 2 * FF, D, 64, 0, G - 12, bid < G - 12 ? bid : -1, E);
;         GEMM(pg8::EpiSwiGLU, XB, W1, 2 * FF, D, 2, 64, 44, bid - 192, E);
;         if (bid >= G - 12) copy_quota(args, fctl, 16, MISC, tid);
.LBB0_121:
	s_cmp_lt_i32 s82, 2
	s_cselect_b64 s[0:1], -1, 0
	s_add_u32 s60, s80, 0x507b100
	s_addc_u32 s61, s81, 0
	s_add_u32 s86, s80, 0x4000
	s_addc_u32 s87, s81, 0
	s_and_b64 s[0:1], s[0:1], s[2:3]
	s_andn2_b64 vcc, exec, s[0:1]
	s_cbranch_vccnz .LBB0_236
	s_add_u32 s4, s80, 0x8000
	s_addc_u32 s5, s81, 0
	s_add_u32 s30, s80, 0x2f7b100
	s_addc_u32 s31, s81, 0
	s_add_u32 s33, s80, 0x7b100
	s_addc_u32 s34, s81, 0
	s_add_i32 s35, s58, -48
	s_cmp_ge_i32 s96, s35
	s_cselect_b64 s[2:3], -1, 0
	s_cmp_lt_i32 s96, s35
	s_cselect_b32 s36, s96, -1
	s_cmp_gt_i32 s36, -1
	s_cselect_b64 s[6:7], -1, 0
	s_cmp_lt_i32 s36, s35
	s_cselect_b64 s[8:9], -1, 0
	s_and_b64 s[8:9], s[6:7], s[8:9]
	s_and_b64 s[8:9], s[8:9], exec
	s_cselect_b32 s8, 0x580, 0
	s_cmp_lt_u32 s36, s8
	s_cselect_b64 s[10:11], -1, 0
	v_mov_b32_e32 v11, v0
	s_and_b64 s[6:7], s[6:7], s[10:11]
	s_andn2_b64 vcc, exec, s[6:7]
	v_readfirstlane_b32 s6, v11
	s_cbranch_vccnz .LBB0_138
	v_lshlrev_b32_e32 v2, 4, v11
	v_add_u32_e32 v3, 0x2000, v2
	v_ashrrev_i32_e32 v4, 31, v3
	v_lshrrev_b32_e32 v4, 22, v4
	v_add_u32_e32 v4, v3, v4
	v_ashrrev_i32_e32 v10, 10, v4
	v_mul_i32_i24_e32 v5, 0x400, v10
	v_sub_u32_e32 v3, v3, v5
	v_lshrrev_b32_e32 v5, 4, v3
	v_bitop3_b32 v3, v5, v3, 32 bitop3:0x6c
	v_ashrrev_i32_e32 v5, 31, v3
	v_lshrrev_b32_e32 v5, 26, v5
	v_add_u32_e32 v5, v3, v5
	v_ashrrev_i32_e32 v12, 6, v5
	v_and_b32_e32 v5, 0xc0, v5
	v_sub_u32_e32 v3, v3, v5
	v_mov_b32_e32 v5, 1
	v_lshlrev_b32_e32 v4, 5, v10
	v_ashrrev_i16_sdwa v3, v5, sext(v3) dst_sel:DWORD dst_unused:UNUSED_PAD src0_sel:DWORD src1_sel:BYTE_0
	v_and_b32_e32 v4, 32, v4
	v_bfe_i32 v13, v3, 0, 16
	v_add_u32_e32 v3, v4, v13
	v_lshlrev_b32_e32 v4, 3, v10
	v_and_b32_e32 v4, 0x1ffff0, v4
	v_add_lshl_u32 v4, v12, v4, 11
	v_lshl_add_u32 v130, v3, 1, v4
	v_bfe_i32 v4, v11, 27, 1
	v_lshrrev_b32_e32 v4, 22, v4
	v_add_u32_e32 v4, v2, v4
	v_and_b32_e32 v4, 0xfffffc00, v4
	s_lshr_b32 s38, s8, 3
	s_and_b32 s10, s36, 7
	v_sub_u32_e32 v2, v2, v4
	s_lshr_b32 s11, s36, 3
	s_mul_i32 s10, s38, s10
	v_lshrrev_b32_e32 v4, 4, v2
	s_add_i32 s10, s10, s11
	v_bitop3_b32 v2, v4, v2, 32 bitop3:0x6c
	s_and_b32 s11, s10, 0xffff
	v_ashrrev_i32_e32 v4, 31, v2
	s_mul_i32 s11, s11, 0xba2f
	v_ashrrev_i32_e32 v3, 31, v11
	v_lshrrev_b32_e32 v4, 26, v4
	s_lshr_b32 s11, s11, 23
	v_lshrrev_b32_e32 v3, 26, v3
	v_add_u32_e32 v4, v2, v4
	s_lshl_b32 s12, s11, 3
	s_mulk_i32 s11, 0xb0
	v_add_u32_e32 v3, v11, v3
	v_ashrrev_i32_e32 v15, 6, v4
	v_and_b32_e32 v4, 0xc0, v4
	s_sub_i32 s10, s10, s11
	v_ashrrev_i32_e32 v14, 6, v3
	v_sub_u32_e32 v2, v2, v4
	s_and_b32 s11, s10, 7
	v_lshlrev_b32_e32 v3, 5, v14
	v_ashrrev_i16_sdwa v2, v5, sext(v2) dst_sel:DWORD dst_unused:UNUSED_PAD src0_sel:DWORD src1_sel:BYTE_0
	s_or_b32 s11, s11, s12
	s_ashr_i32 s9, s6, 6
	v_and_b32_e32 v3, 32, v3
	v_bfe_i32 v16, v2, 0, 16
	s_and_b32 s48, s11, 0xfff
	s_bfe_u32 s12, s10, 0x50003
	s_ashr_i32 s7, s6, 8
	s_lshl_b32 s37, s9, 10
	v_add_u32_e32 v2, v3, v16
	v_lshlrev_b32_e32 v3, 3, v14
	s_lshl_b32 s13, s48, 19
	s_lshl_b32 s10, s12, 19
	v_and_b32_e32 v3, 0x1ffff0, v3
	s_add_u32 s26, s33, s10
	v_add_lshl_u32 v3, v15, v3, 11
	s_addc_u32 s27, s34, 0
	s_add_i32 s39, s37, 0
	v_lshl_add_u32 v132, v2, 1, v3
	s_add_i32 m0, s39, 0x10000
	v_mov_b32_e32 v133, 0
	global_load_lds_dwordx4 v132, s[26:27]
	s_add_i32 m0, s39, 0x12000
	s_add_u32 s10, s26, 0x40000
	global_load_lds_dwordx4 v130, s[26:27]
	s_addc_u32 s11, s27, 0
	s_add_i32 m0, s39, 0x14000
	v_mov_b32_e32 v131, v133
	global_load_lds_dwordx4 v132, s[10:11]
	s_add_i32 m0, s39, 0x16000
	s_add_u32 s24, s30, s13
	s_addc_u32 s25, s31, 0
	s_add_i32 s40, s39, 0x2000
	global_load_lds_dwordx4 v130, s[10:11]
	s_mov_b32 m0, s39
	s_add_u32 s10, s24, 0x40000
	global_load_lds_dwordx4 v132, s[24:25]
	s_mov_b32 m0, s40
	s_addc_u32 s11, s25, 0
	s_add_i32 s41, s39, 0x4000
	global_load_lds_dwordx4 v130, s[24:25]
	s_mov_b32 m0, s41
	s_add_i32 s42, s39, 0x6000
	global_load_lds_dwordx4 v132, s[10:11]
	s_mov_b32 m0, s42
	s_cmp_eq_u32 s7, 1
	global_load_lds_dwordx4 v130, s[10:11]
	v_lshl_add_u64 v[8:9], s[26:27], 0, v[132:133]
	v_lshl_add_u64 v[6:7], s[26:27], 0, v[130:131]
	v_lshl_add_u64 v[2:3], s[24:25], 0, v[132:133]
	s_cselect_b64 s[10:11], -1, 0
	s_cmp_lg_u32 s7, 1
	v_lshl_add_u64 v[4:5], s[24:25], 0, v[130:131]
	s_cbranch_scc1 .LBB0_125
	s_barrier

; #define GEMM(EPI, Aop, Bop, Nn, Kk, nM_, pmoff, Gs, cs, Eobj) do { pg8::Gemm g_{Aop, Bop, T, Nn, Kk}; pg8::SubOrder S_; S_.init(nM_, (Nn) / 256, pmoff, Gs, cs); \
;         pg8::gemm_phase<EPI, pg8::SubOrder, true, true>(lds, g_, S_, Eobj); } while (0)
;     __host__ __device__ bool next(int i, Unit& u) const {
;         const long L = (long)i * G + c; if (c < 0 || L >= nwg) return false;
;         int wgid = (int)L; { const int q = nwg / NXCD, r = nwg % NXCD, xcd = wgid % NXCD, off = wgid / NXCD; wgid = (xcd < r ? xcd * (q + 1) : r * (q + 1) + (xcd - r) * q) + off; }
;         const int nig = WGM * nN, gid = wgid / nig, fm = gid * WGM, gsz = (nM - fm) < WGM ? (nM - fm) : WGM;
;         u.pm = pm_off + fm + ((wgid % nig) % gsz); u.pn = (wgid % nig) / gsz; return true;
; __global__ void __launch_bounds__(512, 2) mk_fwd(Args args) {
;     ...
;         GEMM(pg8::EpiSwiGLU, XB, W1, 2 * FF, D, 2, 64, 44, bid - 192, E);
.LBB0_138:
	v_mov_b32_e32 v11, v0
	s_add_i32 s9, s96, 0xffffff60
	s_cmp_gt_u32 s9, 43
	v_readfirstlane_b32 s20, v11
	s_cbranch_scc1 .LBB0_150
	s_and_b32 s10, s96, 7
	s_cmp_gt_u32 s10, 3
	s_cbranch_scc0 .LBB0_141
	s_mul_i32 s6, s10, 5
	s_add_i32 s8, s6, 4
	s_cbranch_execz .LBB0_142
	s_branch .LBB0_143

; #define LAS __attribute__((address_space(3)))
; __device__ __forceinline__ void copy_quota(const Args& a, unsigned* ctl, int quota, volatile LAS unsigned* misc, int tid) {
;     for (int k = 0; k < quota; ++k) {
;         if (tid == 0) misc[24 + (k & 1)] = __hip_atomic_fetch_add(ctl, 1u, __ATOMIC_RELAXED, __HIP_MEMORY_SCOPE_AGENT);
;         __syncthreads();
;         const unsigned id = (unsigned)__builtin_amdgcn_readfirstlane((int)misc[24 + (k & 1)]);
;         if (id >= (unsigned)N_CHUNKS) break;
;         copy_chunk(a, (int)id, tid);
;     }
; __global__ void __launch_bounds__(512, 2) mk_fwd(Args args) {
;     ...
;         if (bid >= G - 12) copy_quota(args, fctl, 16, MISC, tid);
.LBB0_152:
	s_or_b64 exec, exec, s[8:9]
	s_add_i32 s49, s49, 1
	s_cmp_eq_u32 s49, 22
	s_cselect_b64 s[8:9], -1, 0
